# GEMM loops: the four LDS read bases of the B-fragment stage buffers precomputed per tile (4 VALU adds per K-iteration removed)
# speedup vs baseline: 1.0109x; 1.0019x over previous
; #define PG8_STAGE(bufoff, gbase, voff) do { _Pragma("unroll") for (int _i = 0; _i < 2; ++_i) \
;         __builtin_amdgcn_global_load_lds((const unsigned*)((const char*)(gbase) + (voff)[_i]), (LAS unsigned*)(lds + (bufoff) + ldsw + _i * 8192), 16, 0, 0); } while (0)
; #define PG8_WAIT_V(n) asm volatile("s_waitcnt vmcnt(" #n ")" ::: "memory")
; template <class Epi>
; DI void gemm_phase(LAS unsigned char* lds, const Gemm g, const StaticOrder& S, const Epi& E, const int tid) {
;     ...
;     Unit cur, nxt; int ui = 0;
;     if (!S.next(0, cur)) return;
;     f32x4 acc[2][2][4][2];
; #pragma unroll
;     for (int a = 0; a < 2; ++a)
; #pragma unroll
;         for (int b = 0; b < 2; ++b)
; #pragma unroll
;             for (int m = 0; m < 4; ++m)
; #pragma unroll
;                 for (int n = 0; n < 2; ++n) acc[a][b][m][n] = (f32x4){0.f, 0.f, 0.f, 0.f};
;     bf16x8 At[4][2], B0[2][2], B1[2][2];
;     const char* cA = (const char*)g.A + (size_t)cur.pm * tstepA; const char* cB = (const char*)g.Bt + (size_t)cur.pn * tstepB;
;     PG8_STAGE(PG8_SB(0, 0), cB, voffB); PG8_STAGE(PG8_SA(0, 0), cA, voffA); PG8_STAGE(PG8_SB(0, 1), cB + hstepB, voffB); PG8_STAGE(PG8_SA(0, 1), cA + hstepA, voffA);
;     if (wr == 1) PG8_BAR;
;     PG8_WAIT_V(4); PG8_BAR;
;     PG8_STAGE(PG8_SB(1, 0), cB + kstep, voffB); PG8_STAGE(PG8_SA(1, 0), cA + PG8_KTA(1), voffA); PG8_STAGE(PG8_SB(1, 1), cB + hstepB + kstep, voffB);
;     PG8_WAIT_V(6); PG8_BAR;
;     for (;;) {
;         const bool has_next = S.next(ui + 1, nxt);
;         const char* nA = has_next ? (const char*)g.A + (size_t)nxt.pm * tstepA : cA; const char* nB = has_next ? (const char*)g.Bt + (size_t)nxt.pn * tstepB : cB;
;         for (int t = 0; t < nt; t += 2) {
;             const bool last = (t == nt - 2);
;             const char* a1 = cA + PG8_KTA(t + 1);
;             const char* a2 = last ? nA : cA + PG8_KTA(t + 2); const char* b2 = last ? nB : cB + (size_t)(t + 2) * kstep;
;             const char* a3 = last ? nA + PG8_KTA(1) : cA + PG8_KTA(t + 3); const char* b3 = b2 + kstep;
;             PG8_LDB(B0, 0, 0); PG8_SCHED; PG8_LDA(At, 0, 0); PG8_STAGE(PG8_SA(1, 1), a1 + hstepA, voffA);
;             PG8_WAIT_L(8); PG8_BAR; PG8_WAIT_L(0); PG8_MMA(0, 0, At, B0); PG8_BAR; PG8_SCHED;
;             PG8_LDB(B1, 0, 1); PG8_STAGE(PG8_SB(0, 0), b2, voffB);
;             PG8_BAR; PG8_WAIT_L(0); PG8_MMA(0, 1, At, B1); PG8_BAR;
.LBB0_61:
	s_ashr_i32 s43, s42, 31
	v_cmp_lt_i64_e32 vcc, s[6:7], v[142:143]
	s_lshl_b64 s[6:7], s[42:43], 20
	s_add_u32 s46, s70, s6
	s_addc_u32 s47, s71, s7
	s_and_b64 s[6:7], vcc, exec
	s_cselect_b32 s30, s47, s45
	s_cselect_b32 s31, s46, s44
	s_ashr_i32 s39, s38, 31
	s_lshl_b64 s[6:7], s[38:39], 20
	s_add_u32 s48, s36, s6
	s_addc_u32 s49, s37, s7
	s_and_b64 s[6:7], vcc, exec
	s_cselect_b32 s39, s49, s5
	s_cselect_b32 s43, s48, s4
	s_add_u32 s64, s31, 0x80
	s_addc_u32 s65, s30, 0
	s_add_u32 s6, s44, 0x80080
	s_addc_u32 s7, s45, 0
	s_add_u32 s66, s4, 0x100
	v_mov_b64_e32 v[2:3], 0
	s_addc_u32 s67, s5, 0
	s_mov_b32 s68, -2
	s_mov_b64 s[4:5], 0
	v_mov_b64_e32 v[4:5], 0
	v_mov_b64_e32 v[6:7], 0
	v_mov_b64_e32 v[8:9], 0
	v_mov_b64_e32 v[10:11], 0
	v_mov_b64_e32 v[12:13], 0
	v_mov_b64_e32 v[14:15], 0
	v_mov_b64_e32 v[16:17], 0
	v_mov_b64_e32 v[18:19], 0
	v_mov_b64_e32 v[20:21], 0
	v_mov_b64_e32 v[22:23], 0
	v_mov_b64_e32 v[24:25], 0
	v_mov_b64_e32 v[26:27], 0
	v_mov_b64_e32 v[28:29], 0
	v_mov_b64_e32 v[30:31], 0
	v_mov_b64_e32 v[32:33], 0
	v_mov_b64_e32 v[34:35], 0
	v_mov_b64_e32 v[36:37], 0
	v_mov_b64_e32 v[38:39], 0
	v_mov_b64_e32 v[40:41], 0
	v_mov_b64_e32 v[42:43], 0
	v_mov_b64_e32 v[44:45], 0
	v_mov_b64_e32 v[46:47], 0
	v_mov_b64_e32 v[48:49], 0
	v_mov_b64_e32 v[50:51], 0
	v_mov_b64_e32 v[52:53], 0
	v_mov_b64_e32 v[54:55], 0
	v_mov_b64_e32 v[56:57], 0
	v_mov_b64_e32 v[58:59], 0
	v_mov_b64_e32 v[60:61], 0
	v_mov_b64_e32 v[62:63], 0
	v_mov_b64_e32 v[64:65], 0
	v_mov_b64_e32 v[66:67], 0
	v_mov_b64_e32 v[68:69], 0
	v_mov_b64_e32 v[70:71], 0
	v_mov_b64_e32 v[72:73], 0
	v_mov_b64_e32 v[74:75], 0
	v_mov_b64_e32 v[76:77], 0
	v_mov_b64_e32 v[78:79], 0
	v_mov_b64_e32 v[80:81], 0
	v_mov_b64_e32 v[82:83], 0
	v_mov_b64_e32 v[84:85], 0
	v_mov_b64_e32 v[86:87], 0
	v_mov_b64_e32 v[88:89], 0
	v_mov_b64_e32 v[90:91], 0
	v_mov_b64_e32 v[92:93], 0
	v_mov_b64_e32 v[94:95], 0
	v_mov_b64_e32 v[96:97], 0
	v_mov_b64_e32 v[98:99], 0
	v_mov_b64_e32 v[100:101], 0
	v_mov_b64_e32 v[102:103], 0
	v_mov_b64_e32 v[104:105], 0
	v_mov_b64_e32 v[106:107], 0
	v_mov_b64_e32 v[108:109], 0
	v_mov_b64_e32 v[110:111], 0
	v_mov_b64_e32 v[112:113], 0
	v_mov_b64_e32 v[114:115], 0
	v_mov_b64_e32 v[116:117], 0
	v_mov_b64_e32 v[118:119], 0
	v_mov_b64_e32 v[120:121], 0
	v_mov_b64_e32 v[122:123], 0
	v_mov_b64_e32 v[124:125], 0
	v_mov_b64_e32 v[126:127], 0
	v_mov_b64_e32 v[128:129], 0
	v_lshl_add_u64 v[144:145], s[6:7], 0, v[138:139]
	v_lshl_add_u64 v[146:147], s[6:7], 0, v[140:141]
	s_add_u32 s6, s44, s4
	s_addc_u32 s7, s45, s5
	s_add_u32 s8, s6, 0x100
	s_addc_u32 s9, s7, 0
	s_add_u32 s69, s66, s4
	s_addc_u32 s78, s67, s5
	s_add_u32 s86, s6, 0x180
	s_addc_u32 s87, s7, 0
	s_cmpk_eq_i32 s4, 0xf00
	s_cselect_b32 s51, s30, s9
	s_cselect_b32 s50, s31, s8
	s_cselect_b32 s7, s39, s78
	s_cselect_b32 s6, s43, s69
	s_cselect_b32 s9, s65, s87
	s_cselect_b32 s8, s64, s86
	s_add_u32 s86, s44, s4
	s_addc_u32 s87, s45, s5
	s_add_u32 s86, s86, 0x80080
	s_addc_u32 s87, s87, 0
	v_add_u32_e32 v241, 0x10000, v150
	v_add_u32_e32 v242, 0x14000, v150
	v_add_u32_e32 v243, 0x18000, v150
	v_add_u32_e32 v244, 0x1c000, v150
.LBB0_62:
	s_add_i32 s69, 0, 0x10000
	ds_read_b128 v[158:161], v241
	ds_read_b128 v[162:165], v241 offset:1024
	ds_read_b128 v[166:169], v241 offset:2048
	ds_read_b128 v[178:181], v241 offset:3072
	s_add_i32 m0, s41, 0xc000
	ds_read_b128 v[182:185], v151
	ds_read_b128 v[186:189], v151 offset:1024
	ds_read_b128 v[190:193], v151 offset:2048
	ds_read_b128 v[194:197], v151 offset:3072
	ds_read_b128 v[198:201], v151 offset:4096
	ds_read_b128 v[202:205], v151 offset:5120
	ds_read_b128 v[206:209], v151 offset:6144
	ds_read_b128 v[210:213], v151 offset:7168
	global_load_lds_dwordx4 v138, s[86:87]
	s_add_i32 m0, s41, 0xe000
	s_nop 0
	global_load_lds_dwordx4 v140, s[86:87]
	s_waitcnt lgkmcnt(8)
	s_barrier
	s_waitcnt lgkmcnt(0)
	s_setprio 1
	s_waitcnt lgkmcnt(0)
	v_mfma_f32_16x16x32_bf16 v[126:129], v[158:161], v[182:185], v[126:129]
	v_mfma_f32_16x16x32_bf16 v[122:125], v[166:169], v[182:185], v[122:125]
	v_mfma_f32_16x16x32_bf16 v[118:121], v[158:161], v[190:193], v[118:121]
	v_mfma_f32_16x16x32_bf16 v[114:117], v[166:169], v[190:193], v[114:117]
	v_mfma_f32_16x16x32_bf16 v[102:105], v[158:161], v[198:201], v[102:105]
	v_mfma_f32_16x16x32_bf16 v[98:101], v[166:169], v[198:201], v[98:101]
	v_mfma_f32_16x16x32_bf16 v[86:89], v[158:161], v[206:209], v[86:89]
	v_mfma_f32_16x16x32_bf16 v[82:85], v[166:169], v[206:209], v[82:85]
	v_mfma_f32_16x16x32_bf16 v[126:129], v[162:165], v[186:189], v[126:129]
	v_mfma_f32_16x16x32_bf16 v[122:125], v[178:181], v[186:189], v[122:125]
	v_mfma_f32_16x16x32_bf16 v[118:121], v[162:165], v[194:197], v[118:121]
	v_mfma_f32_16x16x32_bf16 v[114:117], v[178:181], v[194:197], v[114:117]
	v_mfma_f32_16x16x32_bf16 v[102:105], v[162:165], v[202:205], v[102:105]
	v_mfma_f32_16x16x32_bf16 v[98:101], v[178:181], v[202:205], v[98:101]
	v_mfma_f32_16x16x32_bf16 v[86:89], v[162:165], v[210:213], v[86:89]
	v_mfma_f32_16x16x32_bf16 v[82:85], v[178:181], v[210:213], v[82:85]
	s_setprio 0
	s_barrier
	s_add_i32 s78, 0, 0x14000
	s_add_i32 s69, s69, s26
	ds_read_b128 v[214:217], v242
	ds_read_b128 v[218:221], v242 offset:1024
	ds_read_b128 v[222:225], v242 offset:2048
	ds_read_b128 v[226:229], v242 offset:3072
	s_mov_b32 m0, s69
	s_nop 0
	global_load_lds_dwordx4 v0, s[6:7]
	s_add_i32 m0, s69, 0x2000
	s_nop 0
	global_load_lds_dwordx4 v130, s[6:7]
	s_barrier
; #define PG8_STAGE(bufoff, gbase, voff) do { _Pragma("unroll") for (int _i = 0; _i < 2; ++_i) \
;         __builtin_amdgcn_global_load_lds((const unsigned*)((const char*)(gbase) + (voff)[_i]), (LAS unsigned*)(lds + (bufoff) + ldsw + _i * 8192), 16, 0, 0); } while (0)
; #define PG8_LDA(dst, b, h) do { _Pragma("unroll") for (int m = 0; m < 4; ++m) _Pragma("unroll") for (int k = 0; k < 2; ++k) dst[m][k] = *(const LAS bf16x8*)(lds + PG8_SA(b, h) + aoff + m * 2048 + k * 1024); } while (0)
; #define PG8_LDB(dst, b, h) do { _Pragma("unroll") for (int n = 0; n < 2; ++n) _Pragma("unroll") for (int k = 0; k < 2; ++k) dst[n][k] = *(const LAS bf16x8*)(lds + PG8_SB(b, h) + boff + n * 2048 + k * 1024); } while (0)
; #define PG8_MMA(ai, bj, At, Bt) do { __builtin_amdgcn_s_setprio(1); _Pragma("unroll") for (int m = 0; m < 4; ++m) _Pragma("unroll") for (int n = 0; n < 2; ++n) _Pragma("unroll") for (int k = 0; k < 2; ++k) \
;         acc[ai][bj][m][n] = __builtin_amdgcn_mfma_f32_16x16x32_bf16(Bt[n][k], At[m][k], acc[ai][bj][m][n], 0, 0, 0); __builtin_amdgcn_s_setprio(0); } while (0)
; #define PG8_WAIT_V(n) asm volatile("s_waitcnt vmcnt(" #n ")" ::: "memory")
; #define PG8_WAIT_L(n) asm volatile("s_waitcnt lgkmcnt(" #n ")" ::: "memory")
; #define PG8_BAR __builtin_amdgcn_s_barrier()
; #define PG8_SCHED __builtin_amdgcn_sched_barrier(0)
; template <class Epi>
; DI void gemm_phase(LAS unsigned char* lds, const Gemm g, const StaticOrder& S, const Epi& E, const int tid) {
;     ...
;             PG8_BAR; PG8_WAIT_L(0); PG8_MMA(0, 1, At, B1); PG8_BAR;
;             PG8_LDA(At, 0, 1); PG8_STAGE(PG8_SA(0, 0), a2, voffA);
;             PG8_BAR; PG8_WAIT_L(0); PG8_MMA(1, 0, At, B0); PG8_BAR; PG8_SCHED;
;             PG8_STAGE(PG8_SB(0, 1), b2 + hstepB, voffB);
;             PG8_WAIT_V(6); PG8_BAR; PG8_MMA(1, 1, At, B1); PG8_BAR;
;             PG8_LDB(B0, 1, 0); PG8_SCHED; PG8_LDA(At, 1, 0); PG8_STAGE(PG8_SA(0, 1), a2 + hstepA, voffA);
;             PG8_WAIT_L(8); PG8_BAR; PG8_WAIT_L(0); PG8_MMA(0, 0, At, B0); PG8_BAR; PG8_SCHED;
	s_waitcnt lgkmcnt(0)
	s_setprio 1
	s_waitcnt lgkmcnt(0)
	v_mfma_f32_16x16x32_bf16 v[110:113], v[214:217], v[182:185], v[110:113]
	v_mfma_f32_16x16x32_bf16 v[106:109], v[222:225], v[182:185], v[106:109]
	v_mfma_f32_16x16x32_bf16 v[94:97], v[214:217], v[190:193], v[94:97]
	v_mfma_f32_16x16x32_bf16 v[90:93], v[222:225], v[190:193], v[90:93]
	v_mfma_f32_16x16x32_bf16 v[78:81], v[214:217], v[198:201], v[78:81]
	v_mfma_f32_16x16x32_bf16 v[74:77], v[222:225], v[198:201], v[74:77]
	v_mfma_f32_16x16x32_bf16 v[70:73], v[214:217], v[206:209], v[70:73]
	v_mfma_f32_16x16x32_bf16 v[66:69], v[222:225], v[206:209], v[66:69]
	v_mfma_f32_16x16x32_bf16 v[110:113], v[218:221], v[186:189], v[110:113]
	v_mfma_f32_16x16x32_bf16 v[106:109], v[226:229], v[186:189], v[106:109]
	v_mfma_f32_16x16x32_bf16 v[94:97], v[218:221], v[194:197], v[94:97]
	v_mfma_f32_16x16x32_bf16 v[90:93], v[226:229], v[194:197], v[90:93]
	v_mfma_f32_16x16x32_bf16 v[78:81], v[218:221], v[202:205], v[78:81]
	v_mfma_f32_16x16x32_bf16 v[74:77], v[226:229], v[202:205], v[74:77]
	v_mfma_f32_16x16x32_bf16 v[70:73], v[218:221], v[210:213], v[70:73]
	v_mfma_f32_16x16x32_bf16 v[66:69], v[226:229], v[210:213], v[66:69]
	s_setprio 0
	s_mov_b32 m0, s41
	s_barrier
	ds_read_b128 v[182:185], v151 offset:16384
	ds_read_b128 v[186:189], v151 offset:17408
	ds_read_b128 v[190:193], v151 offset:18432
	ds_read_b128 v[194:197], v151 offset:19456
	ds_read_b128 v[198:201], v151 offset:20480
	ds_read_b128 v[202:205], v151 offset:21504
	ds_read_b128 v[206:209], v151 offset:22528
	ds_read_b128 v[210:213], v151 offset:23552
	global_load_lds_dwordx4 v134, s[50:51]
	s_mov_b32 m0, s55
	s_nop 0
	global_load_lds_dwordx4 v132, s[50:51]
	s_barrier
	s_waitcnt lgkmcnt(0)
	s_setprio 1
	s_waitcnt lgkmcnt(0)
	v_mfma_f32_16x16x32_bf16 v[62:65], v[158:161], v[182:185], v[62:65]
	v_mfma_f32_16x16x32_bf16 v[58:61], v[166:169], v[182:185], v[58:61]
	v_mfma_f32_16x16x32_bf16 v[54:57], v[158:161], v[190:193], v[54:57]
	v_mfma_f32_16x16x32_bf16 v[50:53], v[166:169], v[190:193], v[50:53]
	v_mfma_f32_16x16x32_bf16 v[38:41], v[158:161], v[198:201], v[38:41]
	v_mfma_f32_16x16x32_bf16 v[34:37], v[166:169], v[198:201], v[34:37]
	v_mfma_f32_16x16x32_bf16 v[22:25], v[158:161], v[206:209], v[22:25]
	v_mfma_f32_16x16x32_bf16 v[18:21], v[166:169], v[206:209], v[18:21]
	v_mfma_f32_16x16x32_bf16 v[62:65], v[162:165], v[186:189], v[62:65]
	v_mfma_f32_16x16x32_bf16 v[58:61], v[178:181], v[186:189], v[58:61]
	v_mfma_f32_16x16x32_bf16 v[54:57], v[162:165], v[194:197], v[54:57]
	v_mfma_f32_16x16x32_bf16 v[50:53], v[178:181], v[194:197], v[50:53]
	v_mfma_f32_16x16x32_bf16 v[38:41], v[162:165], v[202:205], v[38:41]
	v_mfma_f32_16x16x32_bf16 v[34:37], v[178:181], v[202:205], v[34:37]
	v_mfma_f32_16x16x32_bf16 v[22:25], v[162:165], v[210:213], v[22:25]
	v_mfma_f32_16x16x32_bf16 v[18:21], v[178:181], v[210:213], v[18:21]
	s_setprio 0
	s_barrier
	s_add_u32 s86, s6, 0x80000
	s_addc_u32 s87, s7, 0
	s_add_i32 s69, s78, s26
	s_mov_b32 m0, s69
	s_nop 0
	global_load_lds_dwordx4 v0, s[86:87]
	s_add_i32 m0, s69, 0x2000
	s_nop 0
	global_load_lds_dwordx4 v130, s[86:87]
	s_waitcnt vmcnt(6)
	s_barrier
	s_setprio 1
	v_mfma_f32_16x16x32_bf16 v[46:49], v[214:217], v[182:185], v[46:49]
	v_mfma_f32_16x16x32_bf16 v[42:45], v[222:225], v[182:185], v[42:45]
	v_mfma_f32_16x16x32_bf16 v[30:33], v[214:217], v[190:193], v[30:33]
	v_mfma_f32_16x16x32_bf16 v[26:29], v[222:225], v[190:193], v[26:29]
	v_mfma_f32_16x16x32_bf16 v[14:17], v[214:217], v[198:201], v[14:17]
	v_mfma_f32_16x16x32_bf16 v[10:13], v[222:225], v[198:201], v[10:13]
	v_mfma_f32_16x16x32_bf16 v[6:9], v[214:217], v[206:209], v[6:9]
	v_mfma_f32_16x16x32_bf16 v[2:5], v[222:225], v[206:209], v[2:5]
	v_mfma_f32_16x16x32_bf16 v[46:49], v[218:221], v[186:189], v[46:49]
	v_mfma_f32_16x16x32_bf16 v[42:45], v[226:229], v[186:189], v[42:45]
	v_mfma_f32_16x16x32_bf16 v[30:33], v[218:221], v[194:197], v[30:33]
	v_mfma_f32_16x16x32_bf16 v[26:29], v[226:229], v[194:197], v[26:29]
	v_mfma_f32_16x16x32_bf16 v[14:17], v[218:221], v[202:205], v[14:17]
	v_mfma_f32_16x16x32_bf16 v[10:13], v[226:229], v[202:205], v[10:13]
	v_mfma_f32_16x16x32_bf16 v[6:9], v[218:221], v[210:213], v[6:9]
	v_mfma_f32_16x16x32_bf16 v[2:5], v[226:229], v[210:213], v[2:5]
	s_setprio 0
	s_add_i32 s69, 0, 0x18000
	s_barrier
	ds_read_b128 v[158:161], v243
	ds_read_b128 v[162:165], v243 offset:1024
	ds_read_b128 v[166:169], v243 offset:2048
	ds_read_b128 v[178:181], v243 offset:3072
	s_add_u32 s50, s50, 0x80000
	s_addc_u32 s51, s51, 0
	s_mov_b32 m0, s56
	s_nop 0
	ds_read_b128 v[182:185], v151 offset:32768
	ds_read_b128 v[186:189], v151 offset:33792
	ds_read_b128 v[190:193], v151 offset:34816
	ds_read_b128 v[194:197], v151 offset:35840
	ds_read_b128 v[198:201], v151 offset:36864
	ds_read_b128 v[202:205], v151 offset:37888
	ds_read_b128 v[206:209], v151 offset:38912
	ds_read_b128 v[210:213], v151 offset:39936
	global_load_lds_dwordx4 v134, s[50:51]
	s_mov_b32 m0, s57
	s_nop 0
	global_load_lds_dwordx4 v132, s[50:51]
	s_waitcnt lgkmcnt(8)
	s_barrier
	s_waitcnt lgkmcnt(0)
	s_setprio 1
	s_waitcnt lgkmcnt(0)
	v_mfma_f32_16x16x32_bf16 v[126:129], v[158:161], v[182:185], v[126:129]
	v_mfma_f32_16x16x32_bf16 v[122:125], v[166:169], v[182:185], v[122:125]
	v_mfma_f32_16x16x32_bf16 v[118:121], v[158:161], v[190:193], v[118:121]
	v_mfma_f32_16x16x32_bf16 v[114:117], v[166:169], v[190:193], v[114:117]
	v_mfma_f32_16x16x32_bf16 v[102:105], v[158:161], v[198:201], v[102:105]
	v_mfma_f32_16x16x32_bf16 v[98:101], v[166:169], v[198:201], v[98:101]
	v_mfma_f32_16x16x32_bf16 v[86:89], v[158:161], v[206:209], v[86:89]
	v_mfma_f32_16x16x32_bf16 v[82:85], v[166:169], v[206:209], v[82:85]
	v_mfma_f32_16x16x32_bf16 v[126:129], v[162:165], v[186:189], v[126:129]
	v_mfma_f32_16x16x32_bf16 v[122:125], v[178:181], v[186:189], v[122:125]
	v_mfma_f32_16x16x32_bf16 v[118:121], v[162:165], v[194:197], v[118:121]
	v_mfma_f32_16x16x32_bf16 v[114:117], v[178:181], v[194:197], v[114:117]
	v_mfma_f32_16x16x32_bf16 v[102:105], v[162:165], v[202:205], v[102:105]
	v_mfma_f32_16x16x32_bf16 v[98:101], v[178:181], v[202:205], v[98:101]
	v_mfma_f32_16x16x32_bf16 v[86:89], v[162:165], v[210:213], v[86:89]
	v_mfma_f32_16x16x32_bf16 v[82:85], v[178:181], v[210:213], v[82:85]
	s_setprio 0
	s_barrier
; #define PG8_STAGE(bufoff, gbase, voff) do { _Pragma("unroll") for (int _i = 0; _i < 2; ++_i) \
;         __builtin_amdgcn_global_load_lds((const unsigned*)((const char*)(gbase) + (voff)[_i]), (LAS unsigned*)(lds + (bufoff) + ldsw + _i * 8192), 16, 0, 0); } while (0)
; #define PG8_LDA(dst, b, h) do { _Pragma("unroll") for (int m = 0; m < 4; ++m) _Pragma("unroll") for (int k = 0; k < 2; ++k) dst[m][k] = *(const LAS bf16x8*)(lds + PG8_SA(b, h) + aoff + m * 2048 + k * 1024); } while (0)
; #define PG8_LDB(dst, b, h) do { _Pragma("unroll") for (int n = 0; n < 2; ++n) _Pragma("unroll") for (int k = 0; k < 2; ++k) dst[n][k] = *(const LAS bf16x8*)(lds + PG8_SB(b, h) + boff + n * 2048 + k * 1024); } while (0)
; #define PG8_MMA(ai, bj, At, Bt) do { __builtin_amdgcn_s_setprio(1); _Pragma("unroll") for (int m = 0; m < 4; ++m) _Pragma("unroll") for (int n = 0; n < 2; ++n) _Pragma("unroll") for (int k = 0; k < 2; ++k) \
;         acc[ai][bj][m][n] = __builtin_amdgcn_mfma_f32_16x16x32_bf16(Bt[n][k], At[m][k], acc[ai][bj][m][n], 0, 0, 0); __builtin_amdgcn_s_setprio(0); } while (0)
; #define PG8_WAIT_V(n) asm volatile("s_waitcnt vmcnt(" #n ")" ::: "memory")
; #define PG8_WAIT_L(n) asm volatile("s_waitcnt lgkmcnt(" #n ")" ::: "memory")
; #define PG8_BAR __builtin_amdgcn_s_barrier()
; #define PG8_SCHED __builtin_amdgcn_sched_barrier(0)
; template <class Epi>
; DI void gemm_phase(LAS unsigned char* lds, const Gemm g, const StaticOrder& S, const Epi& E, const int tid) {
;     ...
;             const bool last = (t == nt - 2);
;             const char* a1 = cA + PG8_KTA(t + 1);
;             const char* a2 = last ? nA : cA + PG8_KTA(t + 2); const char* b2 = last ? nB : cB + (size_t)(t + 2) * kstep;
;             const char* a3 = last ? nA + PG8_KTA(1) : cA + PG8_KTA(t + 3); const char* b3 = b2 + kstep;
;     ...
;             PG8_LDB(B1, 1, 1); PG8_STAGE(PG8_SB(1, 0), b3, voffB);
;             PG8_BAR; PG8_WAIT_L(0); PG8_MMA(0, 1, At, B1); PG8_BAR;
;             PG8_LDA(At, 1, 1); PG8_STAGE(PG8_SA(1, 0), a3, voffA);
;             PG8_BAR; PG8_WAIT_L(0); PG8_MMA(1, 0, At, B0); PG8_BAR; PG8_SCHED;
;             PG8_STAGE(PG8_SB(1, 1), b3 + hstepB, voffB);
;             PG8_WAIT_V(6); PG8_BAR; PG8_MMA(1, 1, At, B1); PG8_BAR;
	s_add_i32 s50, 0, 0x1c000
	s_add_i32 s51, s69, s26
	s_add_u32 s86, s6, s84
	s_addc_u32 s87, s7, s85
	s_mov_b32 m0, s51
	ds_read_b128 v[214:217], v244
	ds_read_b128 v[218:221], v244 offset:1024
	ds_read_b128 v[222:225], v244 offset:2048
	ds_read_b128 v[226:229], v244 offset:3072
	global_load_lds_dwordx4 v0, s[86:87]
	s_add_i32 m0, s51, 0x2000
	s_nop 0
	global_load_lds_dwordx4 v130, s[86:87]
	s_barrier
	s_waitcnt lgkmcnt(0)
	s_setprio 1
	s_waitcnt lgkmcnt(0)
	v_mfma_f32_16x16x32_bf16 v[110:113], v[214:217], v[182:185], v[110:113]
	v_mfma_f32_16x16x32_bf16 v[106:109], v[222:225], v[182:185], v[106:109]
	v_mfma_f32_16x16x32_bf16 v[94:97], v[214:217], v[190:193], v[94:97]
	v_mfma_f32_16x16x32_bf16 v[90:93], v[222:225], v[190:193], v[90:93]
	v_mfma_f32_16x16x32_bf16 v[78:81], v[214:217], v[198:201], v[78:81]
	v_mfma_f32_16x16x32_bf16 v[74:77], v[222:225], v[198:201], v[74:77]
	v_mfma_f32_16x16x32_bf16 v[70:73], v[214:217], v[206:209], v[70:73]
	v_mfma_f32_16x16x32_bf16 v[66:69], v[222:225], v[206:209], v[66:69]
	v_mfma_f32_16x16x32_bf16 v[110:113], v[218:221], v[186:189], v[110:113]
	v_mfma_f32_16x16x32_bf16 v[106:109], v[226:229], v[186:189], v[106:109]
	v_mfma_f32_16x16x32_bf16 v[94:97], v[218:221], v[194:197], v[94:97]
	v_mfma_f32_16x16x32_bf16 v[90:93], v[226:229], v[194:197], v[90:93]
	v_mfma_f32_16x16x32_bf16 v[78:81], v[218:221], v[202:205], v[78:81]
	v_mfma_f32_16x16x32_bf16 v[74:77], v[226:229], v[202:205], v[74:77]
	v_mfma_f32_16x16x32_bf16 v[70:73], v[218:221], v[210:213], v[70:73]
	v_mfma_f32_16x16x32_bf16 v[66:69], v[226:229], v[210:213], v[66:69]
	s_setprio 0
	s_mov_b32 m0, s59
	s_nop 0
	s_barrier
	ds_read_b128 v[182:185], v151 offset:49152
	ds_read_b128 v[186:189], v151 offset:50176
	ds_read_b128 v[190:193], v151 offset:51200
	ds_read_b128 v[194:197], v151 offset:52224
	ds_read_b128 v[198:201], v151 offset:53248
	ds_read_b128 v[202:205], v151 offset:54272
	ds_read_b128 v[206:209], v151 offset:55296
	ds_read_b128 v[210:213], v151 offset:56320
	global_load_lds_dwordx4 v134, s[8:9]
	s_mov_b32 m0, s60
	s_nop 0
	global_load_lds_dwordx4 v132, s[8:9]
	s_barrier
	s_waitcnt lgkmcnt(0)
	s_setprio 1
	s_waitcnt lgkmcnt(0)
	v_mfma_f32_16x16x32_bf16 v[62:65], v[158:161], v[182:185], v[62:65]
	v_mfma_f32_16x16x32_bf16 v[58:61], v[166:169], v[182:185], v[58:61]
	v_mfma_f32_16x16x32_bf16 v[54:57], v[158:161], v[190:193], v[54:57]
	v_mfma_f32_16x16x32_bf16 v[50:53], v[166:169], v[190:193], v[50:53]
	v_mfma_f32_16x16x32_bf16 v[38:41], v[158:161], v[198:201], v[38:41]
	v_mfma_f32_16x16x32_bf16 v[34:37], v[166:169], v[198:201], v[34:37]
	v_mfma_f32_16x16x32_bf16 v[22:25], v[158:161], v[206:209], v[22:25]
	v_mfma_f32_16x16x32_bf16 v[18:21], v[166:169], v[206:209], v[18:21]
	v_mfma_f32_16x16x32_bf16 v[62:65], v[162:165], v[186:189], v[62:65]
	v_mfma_f32_16x16x32_bf16 v[58:61], v[178:181], v[186:189], v[58:61]
	v_mfma_f32_16x16x32_bf16 v[54:57], v[162:165], v[194:197], v[54:57]
	v_mfma_f32_16x16x32_bf16 v[50:53], v[178:181], v[194:197], v[50:53]
	v_mfma_f32_16x16x32_bf16 v[38:41], v[162:165], v[202:205], v[38:41]
	v_mfma_f32_16x16x32_bf16 v[34:37], v[178:181], v[202:205], v[34:37]
	v_mfma_f32_16x16x32_bf16 v[22:25], v[162:165], v[210:213], v[22:25]
	v_mfma_f32_16x16x32_bf16 v[18:21], v[178:181], v[210:213], v[18:21]
	s_setprio 0
	s_barrier
	s_add_u32 s6, s6, 0x80080
	s_addc_u32 s7, s7, 0
	s_add_i32 s8, s50, s26
	s_mov_b32 m0, s8
	s_nop 0
	global_load_lds_dwordx4 v0, s[6:7]
	s_add_i32 m0, s8, 0x2000
	s_nop 0
	global_load_lds_dwordx4 v130, s[6:7]
	s_waitcnt vmcnt(6)
	s_barrier
	s_setprio 1
	v_mfma_f32_16x16x32_bf16 v[46:49], v[214:217], v[182:185], v[46:49]
	v_mfma_f32_16x16x32_bf16 v[42:45], v[222:225], v[182:185], v[42:45]
	v_mfma_f32_16x16x32_bf16 v[30:33], v[214:217], v[190:193], v[30:33]
	v_mfma_f32_16x16x32_bf16 v[26:29], v[222:225], v[190:193], v[26:29]
	v_mfma_f32_16x16x32_bf16 v[14:17], v[214:217], v[198:201], v[14:17]
	v_mfma_f32_16x16x32_bf16 v[10:13], v[222:225], v[198:201], v[10:13]
	v_mfma_f32_16x16x32_bf16 v[6:9], v[214:217], v[206:209], v[6:9]
	v_mfma_f32_16x16x32_bf16 v[2:5], v[222:225], v[206:209], v[2:5]
	v_mfma_f32_16x16x32_bf16 v[46:49], v[218:221], v[186:189], v[46:49]
	v_mfma_f32_16x16x32_bf16 v[42:45], v[226:229], v[186:189], v[42:45]
	v_mfma_f32_16x16x32_bf16 v[30:33], v[218:221], v[194:197], v[30:33]
	v_mfma_f32_16x16x32_bf16 v[26:29], v[226:229], v[194:197], v[26:29]
	v_mfma_f32_16x16x32_bf16 v[14:17], v[218:221], v[202:205], v[14:17]
	v_mfma_f32_16x16x32_bf16 v[10:13], v[226:229], v[202:205], v[10:13]
	v_mfma_f32_16x16x32_bf16 v[6:9], v[218:221], v[210:213], v[6:9]
	v_mfma_f32_16x16x32_bf16 v[2:5], v[226:229], v[210:213], v[2:5]
	s_setprio 0
	s_add_i32 s68, s68, 2
	s_add_u32 s4, s4, 0x100
	s_addc_u32 s5, s5, 0
	s_add_u32 s6, s44, s4
	s_addc_u32 s7, s45, s5
	s_add_u32 s8, s6, 0x100
	s_addc_u32 s9, s7, 0
	s_add_u32 s69, s66, s4
	s_addc_u32 s78, s67, s5
	s_add_u32 s86, s6, 0x180
	s_addc_u32 s87, s7, 0
	s_cmpk_eq_i32 s4, 0xf00
	s_cselect_b32 s51, s30, s9
	s_cselect_b32 s50, s31, s8
	s_cselect_b32 s7, s39, s78
	s_cselect_b32 s6, s43, s69
	s_cselect_b32 s9, s65, s87
	s_cselect_b32 s8, s64, s86
	s_add_u32 s86, s44, s4
	s_addc_u32 s87, s45, s5
	s_add_u32 s86, s86, 0x80080
	s_addc_u32 s87, s87, 0
	s_cmp_gt_u32 s68, 29
	s_barrier
; DI unsigned pk2(float a, float b) { f32x2 v = {a, b}; bf16v2 r = __builtin_convertvector(v, bf16v2); return __builtin_bit_cast(unsigned, r); }
; #define PG8_WAIT_V(n) asm volatile("s_waitcnt vmcnt(" #n ")" ::: "memory")
; #define PG8_BAR __builtin_amdgcn_s_barrier()
;     DI void operator()(const f32x4 (&acc)[2][2][4][2], const Unit& u, int wr, int wc, int fr, int fq) const {
;         if (nt) {
;             unsigned char* tb = (unsigned char*)O + ((size_t)(u.pm * nt + u.pn) << 17) + (wr * 4 + wc) * 1024 + (fq * 16 + fr) * 16;
; #pragma unroll
;             for (int ai = 0; ai < 2; ++ai)
; #pragma unroll
;                 for (int m = 0; m < 4; ++m)
; #pragma unroll
;                     for (int bj = 0; bj < 2; ++bj) { const f32x4 v0 = acc[ai][bj][m][0], v1 = acc[ai][bj][m][1];
;                         u32x4 w; w.x = pk2(v0[0], v0[1]); w.y = pk2(v0[2], v0[3]); w.z = pk2(v1[0], v1[1]); w.w = pk2(v1[2], v1[3]);
;                         *(u32x4*)(tb + ((ai * 4 + m) * 2 + bj) * 8192) = w; }
;             return;
; template <class Epi>
; DI void gemm_phase(LAS unsigned char* lds, const Gemm g, const StaticOrder& S, const Epi& E, const int tid) {
;     ...
;         E(acc, cur, wr, wc, fr, fq);
;         if (!has_next) break;
; #pragma unroll
;         for (int a = 0; a < 2; ++a)
; #pragma unroll
;             for (int b = 0; b < 2; ++b)
; #pragma unroll
;                 for (int m = 0; m < 4; ++m)
; #pragma unroll
;                     for (int n = 0; n < 2; ++n) acc[a][b][m][n] = (f32x4){0.f, 0.f, 0.f, 0.f};
;         cur = nxt; cA = nA; cB = nB; ++ui;
;     }
;     PG8_WAIT_V(0);
;     if (wr == 0) PG8_BAR;
;     PG8_BAR;
	s_cbranch_scc0 .LBB0_62
	s_mul_i32 s4, s40, s58
	s_add_i32 s4, s4, s63
	s_ashr_i32 s5, s4, 31
	s_lshl_b64 s[4:5], s[4:5], 17
	v_lshl_add_u64 v[144:145], v[136:137], 0, s[4:5]
	s_movk_i32 s4, 0x2000
	v_cvt_pk_bf16_f32 v110, v110, v111
	v_cvt_pk_bf16_f32 v111, v112, v113
	v_cvt_pk_bf16_f32 v112, v106, v107
	v_add_co_u32_e32 v106, vcc, s4, v144
	v_cvt_pk_bf16_f32 v113, v108, v109
	s_nop 0
	v_addc_co_u32_e32 v107, vcc, 0, v145, vcc
	global_store_dwordx4 v[106:107], v[110:113], off
	s_movk_i32 s4, 0x6000
	v_cvt_pk_bf16_f32 v94, v94, v95
	v_add_co_u32_e32 v110, vcc, s3, v144
	v_cvt_pk_bf16_f32 v95, v96, v97
	s_nop 0
	v_addc_co_u32_e32 v111, vcc, 0, v145, vcc
	v_cvt_pk_bf16_f32 v96, v90, v91
	v_add_co_u32_e32 v90, vcc, s4, v144
	v_cvt_pk_bf16_f32 v97, v92, v93
	s_nop 0
	v_addc_co_u32_e32 v91, vcc, 0, v145, vcc
	s_mov_b32 s4, 0x8000
	global_store_dwordx4 v[90:91], v[94:97], off
	v_cvt_pk_bf16_f32 v78, v78, v79
	v_cvt_pk_bf16_f32 v79, v80, v81
	v_add_co_u32_e32 v94, vcc, s4, v144
	s_mov_b32 s4, 0xa000
	s_nop 0
	v_addc_co_u32_e32 v95, vcc, 0, v145, vcc
	v_cvt_pk_bf16_f32 v80, v74, v75
	v_add_co_u32_e32 v74, vcc, s4, v144
	v_cvt_pk_bf16_f32 v81, v76, v77
	s_nop 0
	v_addc_co_u32_e32 v75, vcc, 0, v145, vcc
	global_store_dwordx4 v[74:75], v[78:81], off
	s_mov_b32 s4, 0xe000
	v_cvt_pk_bf16_f32 v70, v70, v71
	v_add_co_u32_e32 v78, vcc, s13, v144
	v_cvt_pk_bf16_f32 v71, v72, v73
	s_nop 0
	v_addc_co_u32_e32 v79, vcc, 0, v145, vcc
	v_cvt_pk_bf16_f32 v72, v66, v67
	v_add_co_u32_e32 v66, vcc, s4, v144
	s_mov_b32 s4, 0x10000
	s_nop 0
	v_addc_co_u32_e32 v67, vcc, 0, v145, vcc
	v_cvt_pk_bf16_f32 v62, v62, v63
	v_cvt_pk_bf16_f32 v63, v64, v65
	v_cvt_pk_bf16_f32 v64, v58, v59
	v_add_co_u32_e32 v58, vcc, s4, v144
	s_mov_b32 s4, 0x12000
	s_nop 0
	v_addc_co_u32_e32 v59, vcc, 0, v145, vcc
	v_cvt_pk_bf16_f32 v46, v46, v47
	v_cvt_pk_bf16_f32 v47, v48, v49
	v_cvt_pk_bf16_f32 v48, v42, v43
	v_add_co_u32_e32 v42, vcc, s4, v144
	v_cvt_pk_bf16_f32 v49, v44, v45
	s_nop 0
	v_addc_co_u32_e32 v43, vcc, 0, v145, vcc
	s_mov_b32 s4, 0x14000
	global_store_dwordx4 v[42:43], v[46:49], off
	v_cvt_pk_bf16_f32 v30, v30, v31
	v_cvt_pk_bf16_f32 v31, v32, v33
	v_add_co_u32_e32 v46, vcc, s4, v144
	s_mov_b32 s4, 0x16000
	s_nop 0
	v_addc_co_u32_e32 v47, vcc, 0, v145, vcc
	v_cvt_pk_bf16_f32 v32, v26, v27
	v_add_co_u32_e32 v26, vcc, s4, v144
	v_cvt_pk_bf16_f32 v33, v28, v29
	s_nop 0
	v_addc_co_u32_e32 v27, vcc, 0, v145, vcc
	s_mov_b32 s4, 0x18000
	global_store_dwordx4 v[26:27], v[30:33], off
	v_cvt_pk_bf16_f32 v14, v14, v15
	v_cvt_pk_bf16_f32 v15, v16, v17
	v_add_co_u32_e32 v30, vcc, s4, v144
	s_mov_b32 s4, 0x1a000
	s_nop 0
	v_addc_co_u32_e32 v31, vcc, 0, v145, vcc
	v_cvt_pk_bf16_f32 v16, v10, v11
	v_add_co_u32_e32 v10, vcc, s4, v144
	v_cvt_pk_bf16_f32 v17, v12, v13
	s_nop 0
	v_addc_co_u32_e32 v11, vcc, 0, v145, vcc
	s_mov_b32 s4, 0x1c000
	global_store_dwordx4 v[10:11], v[14:17], off
	v_cvt_pk_bf16_f32 v6, v6, v7
	v_cvt_pk_bf16_f32 v7, v8, v9
	v_add_co_u32_e32 v14, vcc, s4, v144
	v_cvt_pk_bf16_f32 v8, v2, v3
	s_nop 0
	v_addc_co_u32_e32 v15, vcc, 0, v145, vcc
	v_add_co_u32_e32 v2, vcc, 0x1e000, v144
	v_cvt_pk_bf16_f32 v126, v126, v127
	s_nop 0
	v_addc_co_u32_e32 v3, vcc, 0, v145, vcc
	v_cvt_pk_bf16_f32 v127, v128, v129
	v_cvt_pk_bf16_f32 v128, v122, v123
	v_cvt_pk_bf16_f32 v129, v124, v125
	v_cvt_pk_bf16_f32 v106, v118, v119
	v_cvt_pk_bf16_f32 v107, v120, v121
	v_cvt_pk_bf16_f32 v108, v114, v115
	v_cvt_pk_bf16_f32 v109, v116, v117
	v_cvt_pk_bf16_f32 v90, v102, v103
	v_cvt_pk_bf16_f32 v91, v104, v105
	v_cvt_pk_bf16_f32 v92, v98, v99
	v_cvt_pk_bf16_f32 v93, v100, v101
	v_cvt_pk_bf16_f32 v74, v86, v87
	v_cvt_pk_bf16_f32 v75, v88, v89
	v_cvt_pk_bf16_f32 v76, v82, v83
	v_cvt_pk_bf16_f32 v77, v84, v85
	v_cvt_pk_bf16_f32 v73, v68, v69
	v_cvt_pk_bf16_f32 v65, v60, v61
	v_cvt_pk_bf16_f32 v42, v54, v55
	v_cvt_pk_bf16_f32 v43, v56, v57
	v_cvt_pk_bf16_f32 v44, v50, v51
	v_cvt_pk_bf16_f32 v45, v52, v53
	v_cvt_pk_bf16_f32 v26, v38, v39
	v_cvt_pk_bf16_f32 v27, v40, v41
	v_cvt_pk_bf16_f32 v28, v34, v35
	v_cvt_pk_bf16_f32 v29, v36, v37
	v_cvt_pk_bf16_f32 v10, v22, v23
	v_cvt_pk_bf16_f32 v11, v24, v25
	v_cvt_pk_bf16_f32 v12, v18, v19
	v_cvt_pk_bf16_f32 v13, v20, v21
	v_cvt_pk_bf16_f32 v9, v4, v5
	s_and_b64 vcc, exec, s[34:35]
	s_mov_b32 s63, s38
	s_mov_b32 s40, s42
	s_mov_b64 s[4:5], s[48:49]
	s_mov_b64 s[44:45], s[46:47]
	global_store_dwordx4 v[144:145], v[126:129], off
	global_store_dwordx4 v[110:111], v[106:109], off
	global_store_dwordx4 v[94:95], v[90:93], off
	global_store_dwordx4 v[78:79], v[74:77], off
	global_store_dwordx4 v[66:67], v[70:73], off
	global_store_dwordx4 v[58:59], v[62:65], off
	global_store_dwordx4 v[46:47], v[42:45], off
	global_store_dwordx4 v[30:31], v[26:29], off
	global_store_dwordx4 v[14:15], v[10:13], off
	global_store_dwordx4 v[2:3], v[6:9], off
	s_cbranch_vccz .LBB0_59
	s_waitcnt vmcnt(0)
	s_cmpk_gt_u32 s25, 0xff
	s_cbranch_scc1 .LBB0_66
	s_barrier

; #define PG8_STAGE(bufoff, gbase, voff) do { _Pragma("unroll") for (int _i = 0; _i < 2; ++_i) \
;         __builtin_amdgcn_global_load_lds((const unsigned*)((const char*)(gbase) + (voff)[_i]), (LAS unsigned*)(lds + (bufoff) + ldsw + _i * 8192), 16, 0, 0); } while (0)
; #define PG8_LDA(dst, b, h) do { _Pragma("unroll") for (int m = 0; m < 4; ++m) _Pragma("unroll") for (int k = 0; k < 2; ++k) dst[m][k] = *(const LAS bf16x8*)(lds + PG8_SA(b, h) + aoff + m * 2048 + k * 1024); } while (0)
; #define PG8_LDB(dst, b, h) do { _Pragma("unroll") for (int n = 0; n < 2; ++n) _Pragma("unroll") for (int k = 0; k < 2; ++k) dst[n][k] = *(const LAS bf16x8*)(lds + PG8_SB(b, h) + boff + n * 2048 + k * 1024); } while (0)
; #define PG8_MMA(ai, bj, At, Bt) do { __builtin_amdgcn_s_setprio(1); _Pragma("unroll") for (int m = 0; m < 4; ++m) _Pragma("unroll") for (int n = 0; n < 2; ++n) _Pragma("unroll") for (int k = 0; k < 2; ++k) \
;         acc[ai][bj][m][n] = __builtin_amdgcn_mfma_f32_16x16x32_bf16(Bt[n][k], At[m][k], acc[ai][bj][m][n], 0, 0, 0); __builtin_amdgcn_s_setprio(0); } while (0)
; #define PG8_WAIT_L(n) asm volatile("s_waitcnt lgkmcnt(" #n ")" ::: "memory")
; #define PG8_BAR __builtin_amdgcn_s_barrier()
; template <class Epi>
; DI void gemm_phase(LAS unsigned char* lds, const Gemm g, const StaticOrder& S, const Epi& E, const int tid) {
;     ...
;         for (int t = 0; t < nt; t += 2) {
;             const bool last = (t == nt - 2);
;             const char* a1 = cA + PG8_KTA(t + 1);
;             const char* a2 = last ? nA : cA + PG8_KTA(t + 2); const char* b2 = last ? nB : cB + (size_t)(t + 2) * kstep;
;             const char* a3 = last ? nA + PG8_KTA(1) : cA + PG8_KTA(t + 3); const char* b3 = b2 + kstep;
;             PG8_LDB(B0, 0, 0); PG8_SCHED; PG8_LDA(At, 0, 0); PG8_STAGE(PG8_SA(1, 1), a1 + hstepA, voffA);
;             PG8_WAIT_L(8); PG8_BAR; PG8_WAIT_L(0); PG8_MMA(0, 0, At, B0); PG8_BAR; PG8_SCHED;
;             PG8_LDB(B1, 0, 1); PG8_STAGE(PG8_SB(0, 0), b2, voffB);
;             PG8_BAR; PG8_WAIT_L(0); PG8_MMA(0, 1, At, B1); PG8_BAR;
;     ...
;         for (int a = 0; a < 2; ++a)
; #pragma unroll
;             for (int b = 0; b < 2; ++b)
; #pragma unroll
;                 for (int m = 0; m < 4; ++m)
; #pragma unroll
;                     for (int n = 0; n < 2; ++n) acc[a][b][m][n] = (f32x4){0.f, 0.f, 0.f, 0.f};
;         cur = nxt; cA = nA; cB = nB; ++ui;
.LBB0_285:
	s_ashr_i32 s41, s40, 31
	s_lshl_b64 s[6:7], s[40:41], 20
	s_add_u32 s44, s34, s6
	s_addc_u32 s45, s35, s7
	s_and_b64 s[6:7], s[38:39], exec
	s_cselect_b32 s30, s45, s5
	s_cselect_b32 s31, s44, s4
	s_add_u32 s38, s4, 0x100
	v_mov_b64_e32 v[2:3], 0
	s_addc_u32 s39, s5, 0
	s_movk_i32 s41, 0x3000
	s_mov_b32 s56, 0x18000
	s_mov_b32 s57, -2
	v_mov_b64_e32 v[4:5], 0
	v_mov_b64_e32 v[6:7], 0
	v_mov_b64_e32 v[8:9], 0
	v_mov_b64_e32 v[10:11], 0
	v_mov_b64_e32 v[12:13], 0
	v_mov_b64_e32 v[14:15], 0
	v_mov_b64_e32 v[16:17], 0
	v_mov_b64_e32 v[18:19], 0
	v_mov_b64_e32 v[20:21], 0
	v_mov_b64_e32 v[22:23], 0
	v_mov_b64_e32 v[24:25], 0
	v_mov_b64_e32 v[26:27], 0
	v_mov_b64_e32 v[28:29], 0
	v_mov_b64_e32 v[30:31], 0
	v_mov_b64_e32 v[32:33], 0
	v_mov_b64_e32 v[34:35], 0
	v_mov_b64_e32 v[36:37], 0
	v_mov_b64_e32 v[38:39], 0
	v_mov_b64_e32 v[40:41], 0
	v_mov_b64_e32 v[42:43], 0
	v_mov_b64_e32 v[44:45], 0
	v_mov_b64_e32 v[46:47], 0
	v_mov_b64_e32 v[48:49], 0
	v_mov_b64_e32 v[50:51], 0
	v_mov_b64_e32 v[52:53], 0
	v_mov_b64_e32 v[54:55], 0
	v_mov_b64_e32 v[56:57], 0
	v_mov_b64_e32 v[58:59], 0
	v_mov_b64_e32 v[60:61], 0
	v_mov_b64_e32 v[62:63], 0
	v_mov_b64_e32 v[64:65], 0
	v_mov_b64_e32 v[66:67], 0
	v_mov_b64_e32 v[68:69], 0
	v_mov_b64_e32 v[70:71], 0
	v_mov_b64_e32 v[72:73], 0
	v_mov_b64_e32 v[74:75], 0
	v_mov_b64_e32 v[76:77], 0
	v_mov_b64_e32 v[78:79], 0
	v_mov_b64_e32 v[80:81], 0
	v_mov_b64_e32 v[82:83], 0
	v_mov_b64_e32 v[84:85], 0
	v_mov_b64_e32 v[86:87], 0
	v_mov_b64_e32 v[88:89], 0
	v_mov_b64_e32 v[90:91], 0
	v_mov_b64_e32 v[92:93], 0
	v_mov_b64_e32 v[94:95], 0
	v_mov_b64_e32 v[96:97], 0
	v_mov_b64_e32 v[98:99], 0
	v_mov_b64_e32 v[100:101], 0
	v_mov_b64_e32 v[102:103], 0
	v_mov_b64_e32 v[104:105], 0
	v_mov_b64_e32 v[106:107], 0
	v_mov_b64_e32 v[108:109], 0
	v_mov_b64_e32 v[110:111], 0
	v_mov_b64_e32 v[112:113], 0
	v_mov_b64_e32 v[114:115], 0
	v_mov_b64_e32 v[116:117], 0
	v_mov_b64_e32 v[118:119], 0
	v_mov_b64_e32 v[120:121], 0
	v_mov_b64_e32 v[122:123], 0
	v_mov_b64_e32 v[124:125], 0
	v_mov_b64_e32 v[126:127], 0
	v_mov_b64_e32 v[128:129], 0
	v_add_u32_e32 v241, 0x10000, v139
	v_add_u32_e32 v242, 0x14000, v139
	v_add_u32_e32 v243, 0x18000, v139
	v_add_u32_e32 v244, 0x1c000, v139
	s_branch .LBB0_287
.LBB0_286:
	s_add_i32 s8, s56, 0xfffe8000
	s_add_i32 s9, s41, 0xffffd000
	s_and_b32 s8, s8, 0xe0000
	s_and_b32 s9, s9, 0x2000
	s_or_b32 s58, s9, s8
	s_add_i32 s8, s56, 0xffff8000
	s_add_i32 s9, s41, 0xfffff000
	s_and_b32 s8, s8, 0x1e0000
	s_and_b32 s9, s9, 0x2000
	s_or_b32 s8, s8, s9
	s_add_u32 s8, s0, s8
	s_addc_u32 s9, s1, 0
	s_and_b64 s[6:7], exec, s[6:7]
	s_cselect_b32 s9, s43, s9
	s_cselect_b32 s8, s42, s8
	s_cselect_b32 s7, s30, s39
	s_cselect_b32 s6, s31, s38
	s_add_i32 s60, 0, 0x10000
	ds_read_b128 v[142:145], v241
	ds_read_b128 v[146:149], v241 offset:1024
	ds_read_b128 v[150:153], v241 offset:2048
	ds_read_b128 v[158:161], v241 offset:3072
	s_add_u32 s58, s0, s58
	s_addc_u32 s59, s1, 0
	s_add_u32 s58, s58, 0x10800
	s_addc_u32 s59, s59, 0
	s_add_i32 m0, s29, 0xc000
	ds_read_b128 v[162:165], v141
	ds_read_b128 v[166:169], v141 offset:1024
	ds_read_b128 v[178:181], v141 offset:2048
	ds_read_b128 v[182:185], v141 offset:3072
	ds_read_b128 v[186:189], v141 offset:4096
	ds_read_b128 v[190:193], v141 offset:5120
	ds_read_b128 v[194:197], v141 offset:6144
	ds_read_b128 v[198:201], v141 offset:7168
	global_load_lds_dwordx4 v130, s[58:59]
	s_add_i32 m0, s29, 0xe000
	s_nop 0
	global_load_lds_dwordx4 v132, s[58:59]
	s_waitcnt lgkmcnt(8)
	s_barrier
	s_waitcnt lgkmcnt(0)
	s_setprio 1
	s_waitcnt lgkmcnt(0)
	v_mfma_f32_16x16x32_bf16 v[126:129], v[142:145], v[162:165], v[126:129]
	v_mfma_f32_16x16x32_bf16 v[122:125], v[150:153], v[162:165], v[122:125]
	v_mfma_f32_16x16x32_bf16 v[118:121], v[142:145], v[178:181], v[118:121]
	v_mfma_f32_16x16x32_bf16 v[114:117], v[150:153], v[178:181], v[114:117]
	v_mfma_f32_16x16x32_bf16 v[102:105], v[142:145], v[186:189], v[102:105]
	v_mfma_f32_16x16x32_bf16 v[98:101], v[150:153], v[186:189], v[98:101]
	v_mfma_f32_16x16x32_bf16 v[86:89], v[142:145], v[194:197], v[86:89]
	v_mfma_f32_16x16x32_bf16 v[82:85], v[150:153], v[194:197], v[82:85]
	v_mfma_f32_16x16x32_bf16 v[126:129], v[146:149], v[166:169], v[126:129]
	v_mfma_f32_16x16x32_bf16 v[122:125], v[158:161], v[166:169], v[122:125]
	v_mfma_f32_16x16x32_bf16 v[118:121], v[146:149], v[182:185], v[118:121]
	v_mfma_f32_16x16x32_bf16 v[114:117], v[158:161], v[182:185], v[114:117]
	v_mfma_f32_16x16x32_bf16 v[102:105], v[146:149], v[190:193], v[102:105]
	v_mfma_f32_16x16x32_bf16 v[98:101], v[158:161], v[190:193], v[98:101]
	v_mfma_f32_16x16x32_bf16 v[86:89], v[146:149], v[198:201], v[86:89]
	v_mfma_f32_16x16x32_bf16 v[82:85], v[158:161], v[198:201], v[82:85]
	s_setprio 0
	s_barrier
	s_add_i32 s61, 0, 0x14000
	s_add_i32 s58, s60, s28
	ds_read_b128 v[202:205], v242
	ds_read_b128 v[206:209], v242 offset:1024
	ds_read_b128 v[210:213], v242 offset:2048
	ds_read_b128 v[214:217], v242 offset:3072
	s_mov_b32 m0, s58
	s_nop 0
	global_load_lds_dwordx4 v0, s[6:7]
	s_add_i32 m0, s58, 0x2000
	s_nop 0
	global_load_lds_dwordx4 v134, s[6:7]
	s_barrier
; #define PG8_STAGE(bufoff, gbase, voff) do { _Pragma("unroll") for (int _i = 0; _i < 2; ++_i) \
;         __builtin_amdgcn_global_load_lds((const unsigned*)((const char*)(gbase) + (voff)[_i]), (LAS unsigned*)(lds + (bufoff) + ldsw + _i * 8192), 16, 0, 0); } while (0)
; #define PG8_LDA(dst, b, h) do { _Pragma("unroll") for (int m = 0; m < 4; ++m) _Pragma("unroll") for (int k = 0; k < 2; ++k) dst[m][k] = *(const LAS bf16x8*)(lds + PG8_SA(b, h) + aoff + m * 2048 + k * 1024); } while (0)
; #define PG8_LDB(dst, b, h) do { _Pragma("unroll") for (int n = 0; n < 2; ++n) _Pragma("unroll") for (int k = 0; k < 2; ++k) dst[n][k] = *(const LAS bf16x8*)(lds + PG8_SB(b, h) + boff + n * 2048 + k * 1024); } while (0)
; #define PG8_MMA(ai, bj, At, Bt) do { __builtin_amdgcn_s_setprio(1); _Pragma("unroll") for (int m = 0; m < 4; ++m) _Pragma("unroll") for (int n = 0; n < 2; ++n) _Pragma("unroll") for (int k = 0; k < 2; ++k) \
;         acc[ai][bj][m][n] = __builtin_amdgcn_mfma_f32_16x16x32_bf16(Bt[n][k], At[m][k], acc[ai][bj][m][n], 0, 0, 0); __builtin_amdgcn_s_setprio(0); } while (0)
; #define PG8_WAIT_V(n) asm volatile("s_waitcnt vmcnt(" #n ")" ::: "memory")
; #define PG8_WAIT_L(n) asm volatile("s_waitcnt lgkmcnt(" #n ")" ::: "memory")
; #define PG8_BAR __builtin_amdgcn_s_barrier()
; #define PG8_SCHED __builtin_amdgcn_sched_barrier(0)
; template <class Epi>
; DI void gemm_phase(LAS unsigned char* lds, const Gemm g, const StaticOrder& S, const Epi& E, const int tid) {
;     ...
;             PG8_BAR; PG8_WAIT_L(0); PG8_MMA(0, 1, At, B1); PG8_BAR;
;             PG8_LDA(At, 0, 1); PG8_STAGE(PG8_SA(0, 0), a2, voffA);
;             PG8_BAR; PG8_WAIT_L(0); PG8_MMA(1, 0, At, B0); PG8_BAR; PG8_SCHED;
;             PG8_STAGE(PG8_SB(0, 1), b2 + hstepB, voffB);
;             PG8_WAIT_V(6); PG8_BAR; PG8_MMA(1, 1, At, B1); PG8_BAR;
;             PG8_LDB(B0, 1, 0); PG8_SCHED; PG8_LDA(At, 1, 0); PG8_STAGE(PG8_SA(0, 1), a2 + hstepA, voffA);
;             PG8_WAIT_L(8); PG8_BAR; PG8_WAIT_L(0); PG8_MMA(0, 0, At, B0); PG8_BAR; PG8_SCHED;
	s_waitcnt lgkmcnt(0)
	s_setprio 1
	s_waitcnt lgkmcnt(0)
	v_mfma_f32_16x16x32_bf16 v[110:113], v[202:205], v[162:165], v[110:113]
	v_mfma_f32_16x16x32_bf16 v[106:109], v[210:213], v[162:165], v[106:109]
	v_mfma_f32_16x16x32_bf16 v[94:97], v[202:205], v[178:181], v[94:97]
	v_mfma_f32_16x16x32_bf16 v[90:93], v[210:213], v[178:181], v[90:93]
	v_mfma_f32_16x16x32_bf16 v[78:81], v[202:205], v[186:189], v[78:81]
	v_mfma_f32_16x16x32_bf16 v[74:77], v[210:213], v[186:189], v[74:77]
	v_mfma_f32_16x16x32_bf16 v[70:73], v[202:205], v[194:197], v[70:73]
	v_mfma_f32_16x16x32_bf16 v[66:69], v[210:213], v[194:197], v[66:69]
	v_mfma_f32_16x16x32_bf16 v[110:113], v[206:209], v[166:169], v[110:113]
	v_mfma_f32_16x16x32_bf16 v[106:109], v[214:217], v[166:169], v[106:109]
	v_mfma_f32_16x16x32_bf16 v[94:97], v[206:209], v[182:185], v[94:97]
	v_mfma_f32_16x16x32_bf16 v[90:93], v[214:217], v[182:185], v[90:93]
	v_mfma_f32_16x16x32_bf16 v[78:81], v[206:209], v[190:193], v[78:81]
	v_mfma_f32_16x16x32_bf16 v[74:77], v[214:217], v[190:193], v[74:77]
	v_mfma_f32_16x16x32_bf16 v[70:73], v[206:209], v[198:201], v[70:73]
	v_mfma_f32_16x16x32_bf16 v[66:69], v[214:217], v[198:201], v[66:69]
	s_setprio 0
	s_mov_b32 m0, s29
	s_barrier
	ds_read_b128 v[162:165], v141 offset:16384
	ds_read_b128 v[166:169], v141 offset:17408
	ds_read_b128 v[178:181], v141 offset:18432
	ds_read_b128 v[182:185], v141 offset:19456
	ds_read_b128 v[186:189], v141 offset:20480
	ds_read_b128 v[190:193], v141 offset:21504
	ds_read_b128 v[194:197], v141 offset:22528
	ds_read_b128 v[198:201], v141 offset:23552
	global_load_lds_dwordx4 v130, s[8:9]
	s_mov_b32 m0, s46
	s_nop 0
	global_load_lds_dwordx4 v132, s[8:9]
	s_barrier
	s_waitcnt lgkmcnt(0)
	s_setprio 1
	s_waitcnt lgkmcnt(0)
	v_mfma_f32_16x16x32_bf16 v[62:65], v[142:145], v[162:165], v[62:65]
	v_mfma_f32_16x16x32_bf16 v[58:61], v[150:153], v[162:165], v[58:61]
	v_mfma_f32_16x16x32_bf16 v[54:57], v[142:145], v[178:181], v[54:57]
	v_mfma_f32_16x16x32_bf16 v[50:53], v[150:153], v[178:181], v[50:53]
	v_mfma_f32_16x16x32_bf16 v[38:41], v[142:145], v[186:189], v[38:41]
	v_mfma_f32_16x16x32_bf16 v[34:37], v[150:153], v[186:189], v[34:37]
	v_mfma_f32_16x16x32_bf16 v[22:25], v[142:145], v[194:197], v[22:25]
	v_mfma_f32_16x16x32_bf16 v[18:21], v[150:153], v[194:197], v[18:21]
	v_mfma_f32_16x16x32_bf16 v[62:65], v[146:149], v[166:169], v[62:65]
	v_mfma_f32_16x16x32_bf16 v[58:61], v[158:161], v[166:169], v[58:61]
	v_mfma_f32_16x16x32_bf16 v[54:57], v[146:149], v[182:185], v[54:57]
	v_mfma_f32_16x16x32_bf16 v[50:53], v[158:161], v[182:185], v[50:53]
	v_mfma_f32_16x16x32_bf16 v[38:41], v[146:149], v[190:193], v[38:41]
	v_mfma_f32_16x16x32_bf16 v[34:37], v[158:161], v[190:193], v[34:37]
	v_mfma_f32_16x16x32_bf16 v[22:25], v[146:149], v[198:201], v[22:25]
	v_mfma_f32_16x16x32_bf16 v[18:21], v[158:161], v[198:201], v[18:21]
	s_setprio 0
	s_barrier
	s_add_u32 s58, s6, 0x80000
	s_addc_u32 s59, s7, 0
	s_add_i32 s60, s61, s28
	s_mov_b32 m0, s60
	s_nop 0
	global_load_lds_dwordx4 v0, s[58:59]
	s_add_i32 m0, s60, 0x2000
	s_nop 0
	global_load_lds_dwordx4 v134, s[58:59]
	s_waitcnt vmcnt(6)
	s_barrier
	s_setprio 1
	v_mfma_f32_16x16x32_bf16 v[46:49], v[202:205], v[162:165], v[46:49]
	v_mfma_f32_16x16x32_bf16 v[42:45], v[210:213], v[162:165], v[42:45]
	v_mfma_f32_16x16x32_bf16 v[30:33], v[202:205], v[178:181], v[30:33]
	v_mfma_f32_16x16x32_bf16 v[26:29], v[210:213], v[178:181], v[26:29]
	v_mfma_f32_16x16x32_bf16 v[14:17], v[202:205], v[186:189], v[14:17]
	v_mfma_f32_16x16x32_bf16 v[10:13], v[210:213], v[186:189], v[10:13]
	v_mfma_f32_16x16x32_bf16 v[6:9], v[202:205], v[194:197], v[6:9]
	v_mfma_f32_16x16x32_bf16 v[2:5], v[210:213], v[194:197], v[2:5]
	v_mfma_f32_16x16x32_bf16 v[46:49], v[206:209], v[166:169], v[46:49]
	v_mfma_f32_16x16x32_bf16 v[42:45], v[214:217], v[166:169], v[42:45]
	v_mfma_f32_16x16x32_bf16 v[30:33], v[206:209], v[182:185], v[30:33]
	v_mfma_f32_16x16x32_bf16 v[26:29], v[214:217], v[182:185], v[26:29]
	v_mfma_f32_16x16x32_bf16 v[14:17], v[206:209], v[190:193], v[14:17]
	v_mfma_f32_16x16x32_bf16 v[10:13], v[214:217], v[190:193], v[10:13]
	v_mfma_f32_16x16x32_bf16 v[6:9], v[206:209], v[198:201], v[6:9]
	v_mfma_f32_16x16x32_bf16 v[2:5], v[214:217], v[198:201], v[2:5]
	s_setprio 0
	s_add_i32 s58, 0, 0x18000
	s_barrier
	ds_read_b128 v[142:145], v243
	ds_read_b128 v[146:149], v243 offset:1024
	ds_read_b128 v[150:153], v243 offset:2048
	ds_read_b128 v[158:161], v243 offset:3072
	s_add_u32 s8, s8, 0x10000
	s_addc_u32 s9, s9, 0
	s_mov_b32 m0, s47
	ds_read_b128 v[162:165], v141 offset:32768
	ds_read_b128 v[166:169], v141 offset:33792
	ds_read_b128 v[178:181], v141 offset:34816
	ds_read_b128 v[182:185], v141 offset:35840
	ds_read_b128 v[186:189], v141 offset:36864
	ds_read_b128 v[190:193], v141 offset:37888
	ds_read_b128 v[194:197], v141 offset:38912
	ds_read_b128 v[198:201], v141 offset:39936
	global_load_lds_dwordx4 v130, s[8:9]
	s_mov_b32 m0, s48
	s_nop 0
	global_load_lds_dwordx4 v132, s[8:9]
	s_waitcnt lgkmcnt(8)
	s_barrier
; #define PG8_STAGE(bufoff, gbase, voff) do { _Pragma("unroll") for (int _i = 0; _i < 2; ++_i) \
;         __builtin_amdgcn_global_load_lds((const unsigned*)((const char*)(gbase) + (voff)[_i]), (LAS unsigned*)(lds + (bufoff) + ldsw + _i * 8192), 16, 0, 0); } while (0)
; #define PG8_LDA(dst, b, h) do { _Pragma("unroll") for (int m = 0; m < 4; ++m) _Pragma("unroll") for (int k = 0; k < 2; ++k) dst[m][k] = *(const LAS bf16x8*)(lds + PG8_SA(b, h) + aoff + m * 2048 + k * 1024); } while (0)
; #define PG8_LDB(dst, b, h) do { _Pragma("unroll") for (int n = 0; n < 2; ++n) _Pragma("unroll") for (int k = 0; k < 2; ++k) dst[n][k] = *(const LAS bf16x8*)(lds + PG8_SB(b, h) + boff + n * 2048 + k * 1024); } while (0)
; #define PG8_MMA(ai, bj, At, Bt) do { __builtin_amdgcn_s_setprio(1); _Pragma("unroll") for (int m = 0; m < 4; ++m) _Pragma("unroll") for (int n = 0; n < 2; ++n) _Pragma("unroll") for (int k = 0; k < 2; ++k) \
;         acc[ai][bj][m][n] = __builtin_amdgcn_mfma_f32_16x16x32_bf16(Bt[n][k], At[m][k], acc[ai][bj][m][n], 0, 0, 0); __builtin_amdgcn_s_setprio(0); } while (0)
; #define PG8_WAIT_V(n) asm volatile("s_waitcnt vmcnt(" #n ")" ::: "memory")
; #define PG8_WAIT_L(n) asm volatile("s_waitcnt lgkmcnt(" #n ")" ::: "memory")
; #define PG8_BAR __builtin_amdgcn_s_barrier()
; #define PG8_SCHED __builtin_amdgcn_sched_barrier(0)
; template <class Epi>
; DI void gemm_phase(LAS unsigned char* lds, const Gemm g, const StaticOrder& S, const Epi& E, const int tid) {
;     ...
;             PG8_WAIT_L(8); PG8_BAR; PG8_WAIT_L(0); PG8_MMA(0, 0, At, B0); PG8_BAR; PG8_SCHED;
;             PG8_LDB(B1, 1, 1); PG8_STAGE(PG8_SB(1, 0), b3, voffB);
;             PG8_BAR; PG8_WAIT_L(0); PG8_MMA(0, 1, At, B1); PG8_BAR;
;             PG8_LDA(At, 1, 1); PG8_STAGE(PG8_SA(1, 0), a3, voffA);
;             PG8_BAR; PG8_WAIT_L(0); PG8_MMA(1, 0, At, B0); PG8_BAR; PG8_SCHED;
;             PG8_STAGE(PG8_SB(1, 1), b3 + hstepB, voffB);
;             PG8_WAIT_V(6); PG8_BAR; PG8_MMA(1, 1, At, B1); PG8_BAR;
	s_waitcnt lgkmcnt(0)
	s_setprio 1
	s_waitcnt lgkmcnt(0)
	v_mfma_f32_16x16x32_bf16 v[126:129], v[142:145], v[162:165], v[126:129]
	v_mfma_f32_16x16x32_bf16 v[122:125], v[150:153], v[162:165], v[122:125]
	v_mfma_f32_16x16x32_bf16 v[118:121], v[142:145], v[178:181], v[118:121]
	v_mfma_f32_16x16x32_bf16 v[114:117], v[150:153], v[178:181], v[114:117]
	v_mfma_f32_16x16x32_bf16 v[102:105], v[142:145], v[186:189], v[102:105]
	v_mfma_f32_16x16x32_bf16 v[98:101], v[150:153], v[186:189], v[98:101]
	v_mfma_f32_16x16x32_bf16 v[86:89], v[142:145], v[194:197], v[86:89]
	v_mfma_f32_16x16x32_bf16 v[82:85], v[150:153], v[194:197], v[82:85]
	v_mfma_f32_16x16x32_bf16 v[126:129], v[146:149], v[166:169], v[126:129]
	v_mfma_f32_16x16x32_bf16 v[122:125], v[158:161], v[166:169], v[122:125]
	v_mfma_f32_16x16x32_bf16 v[118:121], v[146:149], v[182:185], v[118:121]
	v_mfma_f32_16x16x32_bf16 v[114:117], v[158:161], v[182:185], v[114:117]
	v_mfma_f32_16x16x32_bf16 v[102:105], v[146:149], v[190:193], v[102:105]
	v_mfma_f32_16x16x32_bf16 v[98:101], v[158:161], v[190:193], v[98:101]
	v_mfma_f32_16x16x32_bf16 v[86:89], v[146:149], v[198:201], v[86:89]
	v_mfma_f32_16x16x32_bf16 v[82:85], v[158:161], v[198:201], v[82:85]
	s_setprio 0
	s_barrier
	s_add_i32 s8, 0, 0x1c000
	s_add_i32 s9, s58, s28
	s_add_u32 s58, s6, s84
	s_addc_u32 s59, s7, s85
	s_mov_b32 m0, s9
	ds_read_b128 v[202:205], v244
	ds_read_b128 v[206:209], v244 offset:1024
	ds_read_b128 v[210:213], v244 offset:2048
	ds_read_b128 v[214:217], v244 offset:3072
	global_load_lds_dwordx4 v0, s[58:59]
	s_add_i32 m0, s9, 0x2000
	s_nop 0
	global_load_lds_dwordx4 v134, s[58:59]
	s_barrier
	s_waitcnt lgkmcnt(0)
	s_setprio 1
	s_waitcnt lgkmcnt(0)
	v_mfma_f32_16x16x32_bf16 v[110:113], v[202:205], v[162:165], v[110:113]
	v_mfma_f32_16x16x32_bf16 v[106:109], v[210:213], v[162:165], v[106:109]
	v_mfma_f32_16x16x32_bf16 v[94:97], v[202:205], v[178:181], v[94:97]
	v_mfma_f32_16x16x32_bf16 v[90:93], v[210:213], v[178:181], v[90:93]
	v_mfma_f32_16x16x32_bf16 v[78:81], v[202:205], v[186:189], v[78:81]
	v_mfma_f32_16x16x32_bf16 v[74:77], v[210:213], v[186:189], v[74:77]
	v_mfma_f32_16x16x32_bf16 v[70:73], v[202:205], v[194:197], v[70:73]
	v_mfma_f32_16x16x32_bf16 v[66:69], v[210:213], v[194:197], v[66:69]
	v_mfma_f32_16x16x32_bf16 v[110:113], v[206:209], v[166:169], v[110:113]
	v_mfma_f32_16x16x32_bf16 v[106:109], v[214:217], v[166:169], v[106:109]
	v_mfma_f32_16x16x32_bf16 v[94:97], v[206:209], v[182:185], v[94:97]
	v_mfma_f32_16x16x32_bf16 v[90:93], v[214:217], v[182:185], v[90:93]
	v_mfma_f32_16x16x32_bf16 v[78:81], v[206:209], v[190:193], v[78:81]
	v_mfma_f32_16x16x32_bf16 v[74:77], v[214:217], v[190:193], v[74:77]
	v_mfma_f32_16x16x32_bf16 v[70:73], v[206:209], v[198:201], v[70:73]
	v_mfma_f32_16x16x32_bf16 v[66:69], v[214:217], v[198:201], v[66:69]
	s_setprio 0
	s_add_u32 s58, s4, s96
	s_addc_u32 s59, s5, s97
	s_mov_b32 m0, s49
	s_barrier
	ds_read_b128 v[162:165], v141 offset:49152
	ds_read_b128 v[166:169], v141 offset:50176
	ds_read_b128 v[178:181], v141 offset:51200
	ds_read_b128 v[182:185], v141 offset:52224
	ds_read_b128 v[186:189], v141 offset:53248
	ds_read_b128 v[190:193], v141 offset:54272
	ds_read_b128 v[194:197], v141 offset:55296
	ds_read_b128 v[198:201], v141 offset:56320
	global_load_lds_dwordx4 v130, s[58:59]
	s_mov_b32 m0, s50
	s_nop 0
	global_load_lds_dwordx4 v132, s[58:59]
	s_barrier
	s_waitcnt lgkmcnt(0)
	s_setprio 1
	s_waitcnt lgkmcnt(0)
	v_mfma_f32_16x16x32_bf16 v[62:65], v[142:145], v[162:165], v[62:65]
	v_mfma_f32_16x16x32_bf16 v[58:61], v[150:153], v[162:165], v[58:61]
	v_mfma_f32_16x16x32_bf16 v[54:57], v[142:145], v[178:181], v[54:57]
	v_mfma_f32_16x16x32_bf16 v[50:53], v[150:153], v[178:181], v[50:53]
	v_mfma_f32_16x16x32_bf16 v[38:41], v[142:145], v[186:189], v[38:41]
	v_mfma_f32_16x16x32_bf16 v[34:37], v[150:153], v[186:189], v[34:37]
	v_mfma_f32_16x16x32_bf16 v[22:25], v[142:145], v[194:197], v[22:25]
	v_mfma_f32_16x16x32_bf16 v[18:21], v[150:153], v[194:197], v[18:21]
	v_mfma_f32_16x16x32_bf16 v[62:65], v[146:149], v[166:169], v[62:65]
	v_mfma_f32_16x16x32_bf16 v[58:61], v[158:161], v[166:169], v[58:61]
	v_mfma_f32_16x16x32_bf16 v[54:57], v[146:149], v[182:185], v[54:57]
	v_mfma_f32_16x16x32_bf16 v[50:53], v[158:161], v[182:185], v[50:53]
	v_mfma_f32_16x16x32_bf16 v[38:41], v[146:149], v[190:193], v[38:41]
	v_mfma_f32_16x16x32_bf16 v[34:37], v[158:161], v[190:193], v[34:37]
	v_mfma_f32_16x16x32_bf16 v[22:25], v[146:149], v[198:201], v[22:25]
	v_mfma_f32_16x16x32_bf16 v[18:21], v[158:161], v[198:201], v[18:21]
	s_setprio 0
	s_barrier
	s_add_u32 s4, s6, 0x80080
	s_addc_u32 s5, s7, 0
	s_add_i32 s6, s8, s28
	s_mov_b32 m0, s6
	s_nop 0
	global_load_lds_dwordx4 v0, s[4:5]
	s_add_i32 m0, s6, 0x2000
	s_nop 0
	global_load_lds_dwordx4 v134, s[4:5]
	s_waitcnt vmcnt(6)
	s_barrier
	s_setprio 1
	v_mfma_f32_16x16x32_bf16 v[46:49], v[202:205], v[162:165], v[46:49]
	v_mfma_f32_16x16x32_bf16 v[42:45], v[210:213], v[162:165], v[42:45]
	v_mfma_f32_16x16x32_bf16 v[30:33], v[202:205], v[178:181], v[30:33]
	v_mfma_f32_16x16x32_bf16 v[26:29], v[210:213], v[178:181], v[26:29]
	v_mfma_f32_16x16x32_bf16 v[14:17], v[202:205], v[186:189], v[14:17]
	v_mfma_f32_16x16x32_bf16 v[10:13], v[210:213], v[186:189], v[10:13]
	v_mfma_f32_16x16x32_bf16 v[6:9], v[202:205], v[194:197], v[6:9]
	v_mfma_f32_16x16x32_bf16 v[2:5], v[210:213], v[194:197], v[2:5]
	v_mfma_f32_16x16x32_bf16 v[46:49], v[206:209], v[166:169], v[46:49]
	v_mfma_f32_16x16x32_bf16 v[42:45], v[214:217], v[166:169], v[42:45]
	v_mfma_f32_16x16x32_bf16 v[30:33], v[206:209], v[182:185], v[30:33]
	v_mfma_f32_16x16x32_bf16 v[26:29], v[214:217], v[182:185], v[26:29]
	v_mfma_f32_16x16x32_bf16 v[14:17], v[206:209], v[190:193], v[14:17]
	v_mfma_f32_16x16x32_bf16 v[10:13], v[214:217], v[190:193], v[10:13]
	v_mfma_f32_16x16x32_bf16 v[6:9], v[206:209], v[198:201], v[6:9]
	v_mfma_f32_16x16x32_bf16 v[2:5], v[214:217], v[198:201], v[2:5]
	s_setprio 0
	s_addk_i32 s41, 0x2000
	s_add_i32 s56, s56, 0x10000
	s_add_i32 s57, s57, 2
	s_add_u32 s38, s38, 0x100
	s_addc_u32 s39, s39, 0
	s_cmp_gt_u32 s57, 29
	s_barrier
	s_cbranch_scc1 .LBB0_276
